# qscore epilogue: partner top-16 merge by bitonic top-16 merge (80 VALU) instead of 16 med3 insertions (273 VALU), same sorted output
# speedup vs baseline: 1.0062x; 1.0062x over previous
.LBB0_1859:
	s_ashr_i32 s11, s10, 31
	s_lshl_b64 s[10:11], s[10:11], 18
	v_mov_b32_e32 v32, v206
	s_add_u32 s10, s14, s10
	s_addc_u32 s11, s15, s11
	v_ashrrev_i32_e32 v66, 3, v32
	s_ashr_i32 s9, s8, 31
	v_readlane_b32 s36, v248, 46
	v_ashrrev_i32_e32 v67, 31, v66
	s_lshl_b64 s[8:9], s[8:9], 18
	v_readlane_b32 s50, v248, 60
	v_lshlrev_b64 v[66:67], 11, v[66:67]
	v_lshlrev_b32_e32 v32, 4, v32
	v_readlane_b32 s51, v248, 61
	s_add_u32 s8, s50, s8
	v_lshl_add_u64 v[68:69], s[10:11], 0, v[66:67]
	v_and_b32_e32 v32, 0x70, v32
	s_addc_u32 s9, s51, s9
	v_lshl_add_u64 v[74:75], v[68:69], 0, v[32:33]
	v_lshl_add_u64 v[66:67], s[8:9], 0, v[66:67]
	s_mov_b32 s8, 0x10000
	v_add_co_u32_e32 v70, vcc, s8, v74
	s_mov_b32 s9, 0x20000
	s_nop 0
	v_addc_co_u32_e32 v71, vcc, 0, v75, vcc
	v_add_co_u32_e32 v76, vcc, s9, v74
	s_mov_b32 s10, 0x30000
	s_nop 0
	v_addc_co_u32_e32 v77, vcc, 0, v75, vcc
	v_lshl_add_u64 v[90:91], v[66:67], 0, v[32:33]
	global_load_dwordx4 v[66:69], v[74:75], off
	global_load_dwordx4 v[86:89], v[76:77], off
	v_cvt_pk_bf16_f32 v0, v0, v1
	global_load_dwordx4 v[70:73], v[70:71], off
	v_add_co_u32_e32 v74, vcc, s10, v74
	v_cvt_pk_bf16_f32 v1, v2, v3
	s_nop 0
	v_addc_co_u32_e32 v75, vcc, 0, v75, vcc
	global_load_dwordx4 v[94:97], v[74:75], off
	global_load_dwordx4 v[78:81], v[90:91], off
	v_add_co_u32_e32 v74, vcc, s8, v90
	s_movk_i32 s8, 0x108
	v_mul_lo_u32 v32, v187, s8
	v_lshl_add_u32 v32, v188, 1, v32
	ds_write2_b64 v32, v[126:127], v[128:129] offset1:1
	v_add_u32_e32 v126, 0x1080, v32
	ds_write2_b64 v126, v[102:103], v[104:105] offset1:1
	v_add_u32_e32 v102, 0x2100, v32
	v_addc_co_u32_e32 v75, vcc, 0, v91, vcc
	ds_write2_b64 v102, v[98:99], v[100:101] offset1:1
	v_add_u32_e32 v98, 0x3180, v32
	v_add_co_u32_e32 v82, vcc, s9, v90
	ds_write2_b64 v98, v[110:111], v[112:113] offset1:1
	v_add_u32_e32 v98, 0x4200, v32
	v_addc_co_u32_e32 v83, vcc, 0, v91, vcc
	ds_write2_b64 v98, v[106:107], v[108:109] offset1:1
	v_add_u32_e32 v98, 0x5280, v32
	v_cvt_pk_bf16_f32 v2, v4, v5
	v_and_b32_e32 v4, 31, v186
	s_waitcnt vmcnt(12)
	v_bfe_u32 v131, v186, 5, 1
	v_add_co_u32_e32 v90, vcc, s10, v90
	ds_write2_b64 v98, v[118:119], v[120:121] offset1:1
	v_add_u32_e32 v98, 0x6300, v32
	v_add_u32_e32 v32, 0x7380, v32
	v_mul_u32_u24_e32 v4, 0x108, v4
	v_addc_co_u32_e32 v91, vcc, 0, v91, vcc
	ds_write2_b64 v32, v[122:123], v[124:125] offset1:1
	v_cvt_pk_bf16_f32 v124, v12, v13
	v_lshl_add_u32 v12, v131, 3, v4
	global_load_dwordx4 v[74:77], v[74:75], off
	ds_write2_b64 v98, v[114:115], v[116:117] offset1:1
	global_load_dwordx4 v[82:85], v[82:83], off
	v_cvt_pk_bf16_f32 v3, v6, v7
	global_load_dwordx4 v[90:93], v[90:91], off
	v_cvt_pk_bf16_f32 v122, v8, v9
	v_cvt_pk_bf16_f32 v123, v10, v11
	s_waitcnt lgkmcnt(0)
	s_barrier
	ds_read2_b64 v[4:7], v12 offset1:2
	ds_read2_b64 v[8:11], v12 offset0:4 offset1:6
	v_cvt_pk_bf16_f32 v102, v50, v51
	v_cvt_pk_bf16_f32 v103, v52, v53
	v_cvt_pk_bf16_f32 v104, v54, v55
	v_cvt_pk_bf16_f32 v105, v56, v57
	v_cvt_pk_bf16_f32 v98, v58, v59
	v_cvt_pk_bf16_f32 v99, v60, v61
	v_cvt_pk_bf16_f32 v100, v62, v63
	v_cvt_pk_bf16_f32 v101, v64, v65
	s_waitcnt lgkmcnt(1)
	v_mfma_f32_32x32x16_bf16 v[50:65], v[4:7], v[0:3], 0
	v_cvt_pk_bf16_f32 v125, v14, v15
	ds_read2_b64 v[4:7], v12 offset0:8 offset1:10
	v_cvt_pk_bf16_f32 v118, v16, v17
	v_cvt_pk_bf16_f32 v119, v18, v19
	v_cvt_pk_bf16_f32 v120, v20, v21
	v_cvt_pk_bf16_f32 v121, v22, v23
	v_cvt_pk_bf16_f32 v114, v24, v25
	s_waitcnt lgkmcnt(1)
	v_mfma_f32_32x32x16_bf16 v[50:65], v[8:11], v[122:125], v[50:65]
	v_cvt_pk_bf16_f32 v115, v26, v27
	v_cvt_pk_bf16_f32 v116, v28, v29
	v_cvt_pk_bf16_f32 v117, v30, v31
	v_cvt_pk_bf16_f32 v110, v34, v35
	v_cvt_pk_bf16_f32 v111, v36, v37
	v_cvt_pk_bf16_f32 v112, v38, v39
	v_cvt_pk_bf16_f32 v113, v40, v41
	s_waitcnt lgkmcnt(0)
	v_mfma_f32_32x32x16_bf16 v[50:65], v[4:7], v[118:121], v[50:65]
	ds_read2_b64 v[4:7], v12 offset0:12 offset1:14
	v_cvt_pk_bf16_f32 v106, v42, v43
	v_cvt_pk_bf16_f32 v107, v44, v45
	v_cvt_pk_bf16_f32 v108, v46, v47
	v_cvt_pk_bf16_f32 v109, v48, v49
	v_add_u32_e32 v8, 0x2000, v12
	v_add_u32_e32 v32, 0x6000, v12
	s_waitcnt lgkmcnt(0)
	v_mfma_f32_32x32x16_bf16 v[50:65], v[4:7], v[114:117], v[50:65]
	ds_read2_b64 v[4:7], v12 offset0:16 offset1:18
	ds_read2_b64 v[126:129], v32 offset0:100 offset1:102
	s_movk_i32 s8, 0x7f
	v_and_b32_e32 v130, 63, v186
	v_readlane_b32 s37, v248, 47
	v_readlane_b32 s38, v248, 48
	v_readlane_b32 s39, v248, 49
	s_waitcnt lgkmcnt(1)
	v_mfma_f32_32x32x16_bf16 v[50:65], v[4:7], v[110:113], v[50:65]
	ds_read2_b64 v[4:7], v12 offset0:20 offset1:22
	v_readlane_b32 s40, v248, 50
	v_readlane_b32 s41, v248, 51
	v_readlane_b32 s42, v248, 52
	v_readlane_b32 s43, v248, 53
	v_readlane_b32 s44, v248, 54
	v_readlane_b32 s45, v248, 55
	s_waitcnt lgkmcnt(0)
	v_mfma_f32_32x32x16_bf16 v[50:65], v[4:7], v[106:109], v[50:65]
	ds_read2_b64 v[4:7], v12 offset0:24 offset1:26
	v_readlane_b32 s46, v248, 56
	v_readlane_b32 s47, v248, 57
	v_readlane_b32 s48, v248, 58
	v_readlane_b32 s49, v248, 59
	s_waitcnt lgkmcnt(0)
	v_mfma_f32_32x32x16_bf16 v[50:65], v[4:7], v[102:105], v[50:65]
	ds_read2_b64 v[4:7], v12 offset0:28 offset1:30
	s_waitcnt lgkmcnt(0)
	v_mfma_f32_32x32x16_bf16 v[50:65], v[4:7], v[98:101], v[50:65]
	ds_read2_b64 v[4:7], v8 offset0:32 offset1:34
	s_waitcnt lgkmcnt(0)
	v_mfma_f32_32x32x16_bf16 v[34:49], v[4:7], v[0:3], 0
	ds_read2_b64 v[4:7], v8 offset0:36 offset1:38
	s_nop 7
	v_and_b32_e32 v50, 0xffffff80, v50
	v_and_b32_e32 v51, 0xffffff80, v51
	s_waitcnt lgkmcnt(0)
	v_mfma_f32_32x32x16_bf16 v[34:49], v[4:7], v[122:125], v[34:49]
	ds_read2_b64 v[4:7], v8 offset0:40 offset1:42
	s_waitcnt lgkmcnt(0)
	v_mfma_f32_32x32x16_bf16 v[34:49], v[4:7], v[118:121], v[34:49]
	ds_read2_b64 v[4:7], v8 offset0:44 offset1:46
	s_waitcnt lgkmcnt(0)
	v_mfma_f32_32x32x16_bf16 v[34:49], v[4:7], v[114:117], v[34:49]
	ds_read2_b64 v[4:7], v8 offset0:48 offset1:50
	s_waitcnt lgkmcnt(0)
	v_mfma_f32_32x32x16_bf16 v[34:49], v[4:7], v[110:113], v[34:49]
	ds_read2_b64 v[4:7], v8 offset0:52 offset1:54
	s_waitcnt lgkmcnt(0)
	v_mfma_f32_32x32x16_bf16 v[34:49], v[4:7], v[106:109], v[34:49]
	ds_read2_b64 v[4:7], v8 offset0:56 offset1:58
	s_waitcnt lgkmcnt(0)
	v_mfma_f32_32x32x16_bf16 v[34:49], v[4:7], v[102:105], v[34:49]
	ds_read2_b64 v[4:7], v8 offset0:60 offset1:62
	v_add_u32_e32 v8, 0x4000, v12
	s_waitcnt lgkmcnt(0)
	v_mfma_f32_32x32x16_bf16 v[34:49], v[4:7], v[98:101], v[34:49]
	ds_read2_b64 v[4:7], v8 offset0:64 offset1:66
	s_waitcnt lgkmcnt(0)
	v_mfma_f32_32x32x16_bf16 v[16:31], v[4:7], v[0:3], 0
	ds_read2_b64 v[4:7], v8 offset0:68 offset1:70
	s_nop 7
	v_and_b32_e32 v34, 0xffffff80, v34
	v_and_b32_e32 v35, 0xffffff80, v35
	s_waitcnt lgkmcnt(0)
	v_mfma_f32_32x32x16_bf16 v[16:31], v[4:7], v[122:125], v[16:31]
	ds_read2_b64 v[4:7], v8 offset0:72 offset1:74
	s_waitcnt lgkmcnt(0)
	v_mfma_f32_32x32x16_bf16 v[16:31], v[4:7], v[118:121], v[16:31]
	ds_read2_b64 v[4:7], v8 offset0:76 offset1:78
	s_waitcnt lgkmcnt(0)
	v_mfma_f32_32x32x16_bf16 v[16:31], v[4:7], v[114:117], v[16:31]
	ds_read2_b64 v[4:7], v8 offset0:80 offset1:82
	s_waitcnt lgkmcnt(0)
	v_mfma_f32_32x32x16_bf16 v[16:31], v[4:7], v[110:113], v[16:31]
	ds_read2_b64 v[4:7], v8 offset0:84 offset1:86
	s_waitcnt lgkmcnt(0)
	v_mfma_f32_32x32x16_bf16 v[16:31], v[4:7], v[106:109], v[16:31]
	ds_read2_b64 v[4:7], v8 offset0:88 offset1:90
	s_waitcnt lgkmcnt(0)
	v_mfma_f32_32x32x16_bf16 v[16:31], v[4:7], v[102:105], v[16:31]
	ds_read2_b64 v[4:7], v8 offset0:92 offset1:94
	s_waitcnt lgkmcnt(0)
	v_mfma_f32_32x32x16_bf16 v[16:31], v[4:7], v[98:101], v[16:31]
	ds_read2_b64 v[4:7], v32 offset0:96 offset1:98
	s_waitcnt lgkmcnt(0)
	v_mfma_f32_32x32x16_bf16 v[0:15], v[4:7], v[0:3], 0
	s_nop 8
	v_and_b32_e32 v16, 0xffffff80, v16
	v_and_b32_e32 v17, 0xffffff80, v17
	v_mfma_f32_32x32x16_bf16 v[0:15], v[126:129], v[122:125], v[0:15]
	ds_read2_b64 v[122:125], v32 offset0:104 offset1:106
	s_waitcnt lgkmcnt(0)
	v_mfma_f32_32x32x16_bf16 v[0:15], v[122:125], v[118:121], v[0:15]
	ds_read2_b64 v[118:121], v32 offset0:108 offset1:110
	s_waitcnt lgkmcnt(0)
	v_mfma_f32_32x32x16_bf16 v[0:15], v[118:121], v[114:117], v[0:15]
	ds_read2_b64 v[114:117], v32 offset0:112 offset1:114
	s_waitcnt lgkmcnt(0)
	v_mfma_f32_32x32x16_bf16 v[0:15], v[114:117], v[110:113], v[0:15]
	ds_read2_b64 v[110:113], v32 offset0:116 offset1:118
	s_waitcnt lgkmcnt(0)
	v_mfma_f32_32x32x16_bf16 v[0:15], v[110:113], v[106:109], v[0:15]
	ds_read2_b64 v[106:109], v32 offset0:120 offset1:122
	s_waitcnt lgkmcnt(0)
	v_mfma_f32_32x32x16_bf16 v[0:15], v[106:109], v[102:105], v[0:15]
	ds_read2_b64 v[102:105], v32 offset0:124 offset1:126
	v_lshlrev_b32_e32 v32, 2, v131
	v_bitop3_b32 v50, v50, s8, v32 bitop3:0x36
	s_mov_b32 s8, 0xff61b1e6
	v_sub_u32_e32 v51, v51, v32
	v_add_u32_e32 v51, 0x7e, v51
	v_sub_u32_e32 v34, v34, v32
	s_waitcnt lgkmcnt(0)
	v_mfma_f32_32x32x16_bf16 v[0:15], v[102:105], v[98:101], v[0:15]
	v_med3_f32 v98, v50, s8, s8
	v_max_f32_e32 v50, v50, v50
	v_max_f32_e32 v50, 0xff61b1e6, v50
	v_med3_f32 v99, v98, v98, v51
	v_med3_f32 v98, v50, v98, v51
	v_max_f32_e32 v51, v51, v51
	v_max_f32_e32 v50, v50, v51
	v_and_b32_e32 v51, 0xffffff80, v52
	v_sub_u32_e32 v51, v51, v32
	v_add_u32_e32 v51, 0x7d, v51
	v_med3_f32 v52, v99, v99, v51
	v_med3_f32 v99, v98, v99, v51
	v_med3_f32 v98, v50, v98, v51
	v_max_f32_e32 v51, v51, v51
	v_max_f32_e32 v50, v50, v51
	v_and_b32_e32 v51, 0xffffff80, v53
	v_sub_u32_e32 v51, v51, v32
	v_add_u32_e32 v51, 0x7c, v51
	v_med3_f32 v53, v52, v52, v51
	v_med3_f32 v52, v99, v52, v51
	v_med3_f32 v99, v98, v99, v51
	v_med3_f32 v98, v50, v98, v51
	v_max_f32_e32 v51, v51, v51
	v_max_f32_e32 v50, v50, v51
	v_and_b32_e32 v51, 0xffffff80, v54
	v_sub_u32_e32 v51, v51, v32
	v_add_u32_e32 v51, 0x77, v51
	v_med3_f32 v54, v53, v53, v51
	v_med3_f32 v53, v52, v53, v51
	v_med3_f32 v52, v99, v52, v51
	v_med3_f32 v99, v98, v99, v51
	v_med3_f32 v98, v50, v98, v51
	v_max_f32_e32 v51, v51, v51
	v_max_f32_e32 v50, v50, v51
	v_and_b32_e32 v51, 0xffffff80, v55
	v_sub_u32_e32 v51, v51, v32
	v_add_u32_e32 v51, 0x76, v51
	v_med3_f32 v55, v54, v54, v51
	v_med3_f32 v54, v53, v54, v51
	v_med3_f32 v53, v52, v53, v51
	v_med3_f32 v52, v99, v52, v51
	v_med3_f32 v99, v98, v99, v51
	v_med3_f32 v98, v50, v98, v51
	v_max_f32_e32 v51, v51, v51
	v_max_f32_e32 v50, v50, v51
	v_and_b32_e32 v51, 0xffffff80, v56
	v_sub_u32_e32 v51, v51, v32
	v_add_u32_e32 v51, 0x75, v51
	v_med3_f32 v56, v55, v55, v51
	v_med3_f32 v55, v54, v55, v51
	v_med3_f32 v54, v53, v54, v51
	v_med3_f32 v53, v52, v53, v51
	v_med3_f32 v52, v99, v52, v51
	v_med3_f32 v99, v98, v99, v51
	v_med3_f32 v98, v50, v98, v51
	v_max_f32_e32 v51, v51, v51
	v_max_f32_e32 v50, v50, v51
	v_and_b32_e32 v51, 0xffffff80, v57
	v_sub_u32_e32 v51, v51, v32
	v_add_u32_e32 v51, 0x74, v51
	v_med3_f32 v57, v56, v56, v51
	v_med3_f32 v56, v55, v56, v51
	v_med3_f32 v55, v54, v55, v51
	v_med3_f32 v54, v53, v54, v51
	v_med3_f32 v53, v52, v53, v51
	v_med3_f32 v52, v99, v52, v51
	v_med3_f32 v99, v98, v99, v51
	v_med3_f32 v98, v50, v98, v51
	v_max_f32_e32 v51, v51, v51
	v_max_f32_e32 v50, v50, v51
	v_and_b32_e32 v51, 0xffffff80, v58
	v_sub_u32_e32 v51, v51, v32
	v_add_u32_e32 v51, 0x6f, v51
	v_med3_f32 v58, v57, v57, v51
	v_med3_f32 v57, v56, v57, v51
	v_med3_f32 v56, v55, v56, v51
	v_med3_f32 v55, v54, v55, v51
	v_med3_f32 v54, v53, v54, v51
	v_med3_f32 v53, v52, v53, v51
	v_med3_f32 v52, v99, v52, v51
	v_med3_f32 v99, v98, v99, v51
	v_med3_f32 v98, v50, v98, v51
	v_max_f32_e32 v51, v51, v51
	v_max_f32_e32 v50, v50, v51
	v_and_b32_e32 v51, 0xffffff80, v59
	v_sub_u32_e32 v51, v51, v32
	v_add_u32_e32 v51, 0x6e, v51
	v_med3_f32 v59, v58, v58, v51
	v_med3_f32 v58, v57, v58, v51
	v_med3_f32 v57, v56, v57, v51
	v_med3_f32 v56, v55, v56, v51
	v_med3_f32 v55, v54, v55, v51
	v_med3_f32 v54, v53, v54, v51
	v_med3_f32 v53, v52, v53, v51
	v_med3_f32 v52, v99, v52, v51
	v_med3_f32 v99, v98, v99, v51
	v_med3_f32 v98, v50, v98, v51
	v_max_f32_e32 v51, v51, v51
	v_max_f32_e32 v50, v50, v51
	v_and_b32_e32 v51, 0xffffff80, v60
	v_sub_u32_e32 v51, v51, v32
	v_add_u32_e32 v51, 0x6d, v51
	v_med3_f32 v60, v59, v59, v51
	v_med3_f32 v59, v58, v59, v51
	v_med3_f32 v58, v57, v58, v51
	v_med3_f32 v57, v56, v57, v51
	v_med3_f32 v56, v55, v56, v51
	v_med3_f32 v55, v54, v55, v51
	v_med3_f32 v54, v53, v54, v51
	v_med3_f32 v53, v52, v53, v51
	v_med3_f32 v52, v99, v52, v51
	v_med3_f32 v99, v98, v99, v51
	v_med3_f32 v98, v50, v98, v51
	v_max_f32_e32 v51, v51, v51
	v_max_f32_e32 v50, v50, v51
	v_and_b32_e32 v51, 0xffffff80, v61
	v_sub_u32_e32 v51, v51, v32
	v_add_u32_e32 v51, 0x6c, v51
	v_med3_f32 v61, v60, v60, v51
	v_med3_f32 v60, v59, v60, v51
	v_med3_f32 v59, v58, v59, v51
	v_med3_f32 v58, v57, v58, v51
	v_med3_f32 v57, v56, v57, v51
	v_med3_f32 v56, v55, v56, v51
	v_med3_f32 v55, v54, v55, v51
	v_med3_f32 v54, v53, v54, v51
	v_med3_f32 v53, v52, v53, v51
	v_med3_f32 v52, v99, v52, v51
	v_med3_f32 v99, v98, v99, v51
	v_med3_f32 v98, v50, v98, v51
	v_max_f32_e32 v51, v51, v51
	v_max_f32_e32 v50, v50, v51
	v_and_b32_e32 v51, 0xffffff80, v62
	v_sub_u32_e32 v51, v51, v32
	v_add_u32_e32 v51, 0x67, v51
	v_med3_f32 v62, v61, v61, v51
	v_med3_f32 v61, v60, v61, v51
	v_med3_f32 v60, v59, v60, v51
	v_med3_f32 v59, v58, v59, v51
	v_med3_f32 v58, v57, v58, v51
	v_med3_f32 v57, v56, v57, v51
	v_med3_f32 v56, v55, v56, v51
	v_med3_f32 v55, v54, v55, v51
	v_med3_f32 v54, v53, v54, v51
	v_med3_f32 v53, v52, v53, v51
	v_med3_f32 v52, v99, v52, v51
	v_med3_f32 v99, v98, v99, v51
	v_med3_f32 v98, v50, v98, v51
	v_max_f32_e32 v51, v51, v51
	v_max_f32_e32 v50, v50, v51
	v_and_b32_e32 v51, 0xffffff80, v63
	v_sub_u32_e32 v51, v51, v32
	v_add_u32_e32 v51, 0x66, v51
	v_med3_f32 v63, v62, v62, v51
	v_med3_f32 v62, v61, v62, v51
	v_med3_f32 v61, v60, v61, v51
	v_med3_f32 v60, v59, v60, v51
	v_med3_f32 v59, v58, v59, v51
	v_med3_f32 v58, v57, v58, v51
	v_med3_f32 v57, v56, v57, v51
	v_med3_f32 v56, v55, v56, v51
	v_med3_f32 v55, v54, v55, v51
	v_med3_f32 v54, v53, v54, v51
	v_med3_f32 v53, v52, v53, v51
	v_med3_f32 v52, v99, v52, v51
	v_med3_f32 v99, v98, v99, v51
	v_med3_f32 v98, v50, v98, v51
	v_max_f32_e32 v51, v51, v51
	v_max_f32_e32 v50, v50, v51
	v_and_b32_e32 v51, 0xffffff80, v64
	v_sub_u32_e32 v51, v51, v32
	v_add_u32_e32 v51, 0x65, v51
	v_med3_f32 v64, v63, v63, v51
	v_med3_f32 v63, v62, v63, v51
	v_med3_f32 v62, v61, v62, v51
	v_med3_f32 v61, v60, v61, v51
	v_med3_f32 v60, v59, v60, v51
	v_med3_f32 v59, v58, v59, v51
	v_med3_f32 v58, v57, v58, v51
	v_med3_f32 v57, v56, v57, v51
	v_med3_f32 v56, v55, v56, v51
	v_med3_f32 v55, v54, v55, v51
	v_med3_f32 v54, v53, v54, v51
	v_med3_f32 v53, v52, v53, v51
	v_med3_f32 v52, v99, v52, v51
	v_med3_f32 v99, v98, v99, v51
	v_med3_f32 v98, v50, v98, v51
	v_max_f32_e32 v51, v51, v51
	v_max_f32_e32 v50, v50, v51
	v_and_b32_e32 v51, 0xffffff80, v65
	v_sub_u32_e32 v51, v51, v32
	v_add_u32_e32 v51, 0x64, v51
	v_med3_f32 v64, v63, v64, v51
	v_med3_f32 v63, v62, v63, v51
	v_med3_f32 v62, v61, v62, v51
	v_med3_f32 v61, v60, v61, v51
	v_med3_f32 v60, v59, v60, v51
	v_med3_f32 v59, v58, v59, v51
	v_med3_f32 v58, v57, v58, v51
	v_med3_f32 v57, v56, v57, v51
	v_med3_f32 v56, v55, v56, v51
	v_med3_f32 v55, v54, v55, v51
	v_med3_f32 v54, v53, v54, v51
	v_med3_f32 v53, v52, v53, v51
	v_med3_f32 v52, v99, v52, v51
	v_med3_f32 v65, v98, v99, v51
	v_med3_f32 v98, v50, v98, v51
	v_max_f32_e32 v51, v51, v51
	v_max_f32_e32 v50, v50, v51
	v_add_u32_e32 v34, 0x5f, v34
	v_med3_f32 v51, v63, v64, v34
	v_med3_f32 v63, v62, v63, v34
	v_med3_f32 v62, v61, v62, v34
	v_med3_f32 v61, v60, v61, v34
	v_med3_f32 v60, v59, v60, v34
	v_med3_f32 v59, v58, v59, v34
	v_med3_f32 v58, v57, v58, v34
	v_med3_f32 v57, v56, v57, v34
	v_med3_f32 v56, v55, v56, v34
	v_med3_f32 v55, v54, v55, v34
	v_med3_f32 v54, v53, v54, v34
	v_med3_f32 v53, v52, v53, v34
	v_med3_f32 v52, v65, v52, v34
	v_med3_f32 v64, v98, v65, v34
	v_med3_f32 v65, v50, v98, v34
	v_max_f32_e32 v34, v34, v34
	v_sub_u32_e32 v35, v35, v32
	v_max_f32_e32 v34, v50, v34
	v_add_u32_e32 v35, 0x5e, v35
	v_med3_f32 v50, v63, v51, v35
	v_med3_f32 v51, v62, v63, v35
	v_med3_f32 v62, v61, v62, v35
	v_med3_f32 v61, v60, v61, v35
	v_med3_f32 v60, v59, v60, v35
	v_med3_f32 v59, v58, v59, v35
	v_med3_f32 v58, v57, v58, v35
	v_med3_f32 v57, v56, v57, v35
	v_med3_f32 v56, v55, v56, v35
	v_med3_f32 v55, v54, v55, v35
	v_med3_f32 v54, v53, v54, v35
	v_med3_f32 v53, v52, v53, v35
	v_med3_f32 v52, v64, v52, v35
	v_med3_f32 v63, v65, v64, v35
	v_med3_f32 v64, v34, v65, v35
	v_max_f32_e32 v35, v35, v35
	v_max_f32_e32 v34, v34, v35
	v_and_b32_e32 v35, 0xffffff80, v36
	v_sub_u32_e32 v35, v35, v32
	v_add_u32_e32 v35, 0x5d, v35
	v_med3_f32 v36, v51, v50, v35
	v_med3_f32 v50, v62, v51, v35
	v_med3_f32 v51, v61, v62, v35
	v_med3_f32 v61, v60, v61, v35
	v_med3_f32 v60, v59, v60, v35
	v_med3_f32 v59, v58, v59, v35
	v_med3_f32 v58, v57, v58, v35
	v_med3_f32 v57, v56, v57, v35
	v_med3_f32 v56, v55, v56, v35
	v_med3_f32 v55, v54, v55, v35
	v_med3_f32 v54, v53, v54, v35
	v_med3_f32 v53, v52, v53, v35
	v_med3_f32 v52, v63, v52, v35
	v_med3_f32 v62, v64, v63, v35
	v_med3_f32 v63, v34, v64, v35
	v_max_f32_e32 v35, v35, v35
	v_max_f32_e32 v34, v34, v35
	v_and_b32_e32 v35, 0xffffff80, v37
	v_sub_u32_e32 v35, v35, v32
	v_add_u32_e32 v35, 0x5c, v35
	v_med3_f32 v36, v50, v36, v35
	v_med3_f32 v37, v51, v50, v35
	v_med3_f32 v50, v61, v51, v35
	v_med3_f32 v51, v60, v61, v35
	v_med3_f32 v60, v59, v60, v35
	v_med3_f32 v59, v58, v59, v35
	v_med3_f32 v58, v57, v58, v35
	v_med3_f32 v57, v56, v57, v35
	v_med3_f32 v56, v55, v56, v35
	v_med3_f32 v55, v54, v55, v35
	v_med3_f32 v54, v53, v54, v35
	v_med3_f32 v53, v52, v53, v35
	v_med3_f32 v52, v62, v52, v35
	v_med3_f32 v61, v63, v62, v35
	v_med3_f32 v62, v34, v63, v35
	v_max_f32_e32 v35, v35, v35
	v_max_f32_e32 v34, v34, v35
	v_and_b32_e32 v35, 0xffffff80, v38
	v_sub_u32_e32 v35, v35, v32
	v_add_u32_e32 v35, 0x57, v35
	v_med3_f32 v36, v37, v36, v35
	v_med3_f32 v37, v50, v37, v35
	v_med3_f32 v38, v51, v50, v35
	v_med3_f32 v50, v60, v51, v35
	v_med3_f32 v51, v59, v60, v35
	v_med3_f32 v59, v58, v59, v35
	v_med3_f32 v58, v57, v58, v35
	v_med3_f32 v57, v56, v57, v35
	v_med3_f32 v56, v55, v56, v35
	v_med3_f32 v55, v54, v55, v35
	v_med3_f32 v54, v53, v54, v35
	v_med3_f32 v53, v52, v53, v35
	v_med3_f32 v52, v61, v52, v35
	v_med3_f32 v60, v62, v61, v35
	v_med3_f32 v61, v34, v62, v35
	v_max_f32_e32 v35, v35, v35
	v_max_f32_e32 v34, v34, v35
	v_and_b32_e32 v35, 0xffffff80, v39
	v_sub_u32_e32 v35, v35, v32
	v_add_u32_e32 v35, 0x56, v35
	v_med3_f32 v36, v37, v36, v35
	v_med3_f32 v37, v38, v37, v35
	v_med3_f32 v38, v50, v38, v35
	v_med3_f32 v39, v51, v50, v35
	v_med3_f32 v50, v59, v51, v35
	v_med3_f32 v51, v58, v59, v35
	v_med3_f32 v58, v57, v58, v35
	v_med3_f32 v57, v56, v57, v35
	v_med3_f32 v56, v55, v56, v35
	v_med3_f32 v55, v54, v55, v35
	v_med3_f32 v54, v53, v54, v35
	v_med3_f32 v53, v52, v53, v35
	v_med3_f32 v52, v60, v52, v35
	v_med3_f32 v59, v61, v60, v35
	v_med3_f32 v60, v34, v61, v35
	v_max_f32_e32 v35, v35, v35
	v_max_f32_e32 v34, v34, v35
	v_and_b32_e32 v35, 0xffffff80, v40
	v_sub_u32_e32 v35, v35, v32
	v_add_u32_e32 v35, 0x55, v35
	v_med3_f32 v36, v37, v36, v35
	v_med3_f32 v37, v38, v37, v35
	v_med3_f32 v38, v39, v38, v35
	v_med3_f32 v39, v50, v39, v35
	v_med3_f32 v40, v51, v50, v35
	v_med3_f32 v50, v58, v51, v35
	v_med3_f32 v51, v57, v58, v35
	v_med3_f32 v57, v56, v57, v35
	v_med3_f32 v56, v55, v56, v35
	v_med3_f32 v55, v54, v55, v35
	v_med3_f32 v54, v53, v54, v35
	v_med3_f32 v53, v52, v53, v35
	v_med3_f32 v52, v59, v52, v35
	v_med3_f32 v58, v60, v59, v35
	v_med3_f32 v59, v34, v60, v35
	v_max_f32_e32 v35, v35, v35
	v_max_f32_e32 v34, v34, v35
	v_and_b32_e32 v35, 0xffffff80, v41
	v_sub_u32_e32 v35, v35, v32
	v_add_u32_e32 v35, 0x54, v35
	v_med3_f32 v36, v37, v36, v35
	v_med3_f32 v37, v38, v37, v35
	v_med3_f32 v38, v39, v38, v35
	v_med3_f32 v39, v40, v39, v35
	v_med3_f32 v40, v50, v40, v35
	v_med3_f32 v41, v51, v50, v35
	v_med3_f32 v50, v57, v51, v35
	v_med3_f32 v51, v56, v57, v35
	v_med3_f32 v56, v55, v56, v35
	v_med3_f32 v55, v54, v55, v35
	v_med3_f32 v54, v53, v54, v35
	v_med3_f32 v53, v52, v53, v35
	v_med3_f32 v52, v58, v52, v35
	v_med3_f32 v57, v59, v58, v35
	v_med3_f32 v58, v34, v59, v35
	v_max_f32_e32 v35, v35, v35
	v_max_f32_e32 v34, v34, v35
	v_and_b32_e32 v35, 0xffffff80, v42
	v_sub_u32_e32 v35, v35, v32
	v_add_u32_e32 v35, 0x4f, v35
	v_med3_f32 v36, v37, v36, v35
	v_med3_f32 v37, v38, v37, v35
	v_med3_f32 v38, v39, v38, v35
	v_med3_f32 v39, v40, v39, v35
	v_med3_f32 v40, v41, v40, v35
	v_med3_f32 v41, v50, v41, v35
	v_med3_f32 v42, v51, v50, v35
	v_med3_f32 v50, v56, v51, v35
	v_med3_f32 v51, v55, v56, v35
	v_med3_f32 v55, v54, v55, v35
	v_med3_f32 v54, v53, v54, v35
	v_med3_f32 v53, v52, v53, v35
	v_med3_f32 v52, v57, v52, v35
	v_med3_f32 v56, v58, v57, v35
	v_med3_f32 v57, v34, v58, v35
	v_max_f32_e32 v35, v35, v35
	v_max_f32_e32 v34, v34, v35
	v_and_b32_e32 v35, 0xffffff80, v43
	v_sub_u32_e32 v35, v35, v32
	v_add_u32_e32 v35, 0x4e, v35
	v_med3_f32 v36, v37, v36, v35
	v_med3_f32 v37, v38, v37, v35
	v_med3_f32 v38, v39, v38, v35
	v_med3_f32 v39, v40, v39, v35
	v_med3_f32 v40, v41, v40, v35
	v_med3_f32 v41, v42, v41, v35
	v_med3_f32 v42, v50, v42, v35
	v_med3_f32 v43, v51, v50, v35
	v_med3_f32 v50, v55, v51, v35
	v_med3_f32 v51, v54, v55, v35
	v_med3_f32 v54, v53, v54, v35
	v_med3_f32 v53, v52, v53, v35
	v_med3_f32 v52, v56, v52, v35
	v_med3_f32 v55, v57, v56, v35
	v_med3_f32 v56, v34, v57, v35
	v_max_f32_e32 v35, v35, v35
	v_max_f32_e32 v34, v34, v35
	v_and_b32_e32 v35, 0xffffff80, v44
	v_sub_u32_e32 v35, v35, v32
	v_add_u32_e32 v35, 0x4d, v35
	v_med3_f32 v36, v37, v36, v35
	v_med3_f32 v37, v38, v37, v35
	v_med3_f32 v38, v39, v38, v35
	v_med3_f32 v39, v40, v39, v35
	v_med3_f32 v40, v41, v40, v35
	v_med3_f32 v41, v42, v41, v35
	v_med3_f32 v42, v43, v42, v35
	v_med3_f32 v43, v50, v43, v35
	v_med3_f32 v44, v51, v50, v35
	v_med3_f32 v50, v54, v51, v35
	v_med3_f32 v51, v53, v54, v35
	v_med3_f32 v53, v52, v53, v35
	v_med3_f32 v52, v55, v52, v35
	v_med3_f32 v54, v56, v55, v35
	v_med3_f32 v55, v34, v56, v35
	v_max_f32_e32 v35, v35, v35
	v_max_f32_e32 v34, v34, v35
	v_and_b32_e32 v35, 0xffffff80, v45
	v_sub_u32_e32 v35, v35, v32
	v_add_u32_e32 v35, 0x4c, v35
	v_med3_f32 v36, v37, v36, v35
	v_med3_f32 v37, v38, v37, v35
	v_med3_f32 v38, v39, v38, v35
	v_med3_f32 v39, v40, v39, v35
	v_med3_f32 v40, v41, v40, v35
	v_med3_f32 v41, v42, v41, v35
	v_med3_f32 v42, v43, v42, v35
	v_med3_f32 v43, v44, v43, v35
	v_med3_f32 v44, v50, v44, v35
	v_med3_f32 v45, v51, v50, v35
	v_med3_f32 v50, v53, v51, v35
	v_med3_f32 v51, v52, v53, v35
	v_med3_f32 v52, v54, v52, v35
	v_med3_f32 v53, v55, v54, v35
	v_med3_f32 v54, v34, v55, v35
	v_max_f32_e32 v35, v35, v35
	v_max_f32_e32 v34, v34, v35
	v_and_b32_e32 v35, 0xffffff80, v46
	v_sub_u32_e32 v35, v35, v32
	v_add_u32_e32 v35, 0x47, v35
	v_med3_f32 v36, v37, v36, v35
	v_med3_f32 v37, v38, v37, v35
	v_med3_f32 v38, v39, v38, v35
	v_med3_f32 v39, v40, v39, v35
	v_med3_f32 v40, v41, v40, v35
	v_med3_f32 v41, v42, v41, v35
	v_med3_f32 v42, v43, v42, v35
	v_med3_f32 v43, v44, v43, v35
	v_med3_f32 v44, v45, v44, v35
	v_med3_f32 v45, v50, v45, v35
	v_med3_f32 v46, v51, v50, v35
	v_med3_f32 v50, v52, v51, v35
	v_med3_f32 v51, v53, v52, v35
	v_med3_f32 v52, v54, v53, v35
	v_med3_f32 v53, v34, v54, v35
	v_max_f32_e32 v35, v35, v35
	v_max_f32_e32 v34, v34, v35
	v_and_b32_e32 v35, 0xffffff80, v47
	v_sub_u32_e32 v35, v35, v32
	v_add_u32_e32 v35, 0x46, v35
	v_med3_f32 v36, v37, v36, v35
	v_med3_f32 v37, v38, v37, v35
	v_med3_f32 v38, v39, v38, v35
	v_med3_f32 v39, v40, v39, v35
	v_med3_f32 v40, v41, v40, v35
	v_med3_f32 v41, v42, v41, v35
	v_med3_f32 v42, v43, v42, v35
	v_med3_f32 v43, v44, v43, v35
	v_med3_f32 v44, v45, v44, v35
	v_med3_f32 v45, v46, v45, v35
	v_med3_f32 v46, v50, v46, v35
	v_med3_f32 v47, v51, v50, v35
	v_med3_f32 v50, v52, v51, v35
	v_med3_f32 v51, v53, v52, v35
	v_med3_f32 v52, v34, v53, v35
	v_max_f32_e32 v35, v35, v35
	v_max_f32_e32 v34, v34, v35
	v_and_b32_e32 v35, 0xffffff80, v48
	v_sub_u32_e32 v35, v35, v32
	v_add_u32_e32 v35, 0x45, v35
	v_med3_f32 v36, v37, v36, v35
	v_med3_f32 v37, v38, v37, v35
	v_med3_f32 v38, v39, v38, v35
	v_med3_f32 v39, v40, v39, v35
	v_med3_f32 v40, v41, v40, v35
	v_med3_f32 v41, v42, v41, v35
	v_med3_f32 v42, v43, v42, v35
	v_med3_f32 v43, v44, v43, v35
	v_med3_f32 v44, v45, v44, v35
	v_med3_f32 v45, v46, v45, v35
	v_med3_f32 v46, v47, v46, v35
	v_med3_f32 v47, v50, v47, v35
	v_med3_f32 v48, v51, v50, v35
	v_med3_f32 v50, v52, v51, v35
	v_med3_f32 v51, v34, v52, v35
	v_max_f32_e32 v35, v35, v35
	v_max_f32_e32 v34, v34, v35
	v_and_b32_e32 v35, 0xffffff80, v49
	v_sub_u32_e32 v35, v35, v32
	v_add_u32_e32 v35, 0x44, v35
	v_med3_f32 v36, v37, v36, v35
	v_med3_f32 v37, v38, v37, v35
	v_med3_f32 v38, v39, v38, v35
	v_med3_f32 v39, v40, v39, v35
	v_med3_f32 v40, v41, v40, v35
	v_med3_f32 v41, v42, v41, v35
	v_med3_f32 v42, v43, v42, v35
	v_med3_f32 v43, v44, v43, v35
	v_med3_f32 v44, v45, v44, v35
	v_med3_f32 v45, v46, v45, v35
	v_med3_f32 v46, v47, v46, v35
	v_med3_f32 v47, v48, v47, v35
	v_med3_f32 v48, v50, v48, v35
	v_med3_f32 v49, v51, v50, v35
	v_med3_f32 v50, v34, v51, v35
	v_max_f32_e32 v35, v35, v35
	v_max_f32_e32 v34, v34, v35
	v_bitop3_b32 v16, v16, 63, v32 bitop3:0x36
	v_med3_f32 v35, v37, v36, v16
	v_med3_f32 v36, v38, v37, v16
	v_med3_f32 v37, v39, v38, v16
	v_med3_f32 v38, v40, v39, v16
	v_med3_f32 v39, v41, v40, v16
	v_med3_f32 v40, v42, v41, v16
	v_med3_f32 v41, v43, v42, v16
	v_med3_f32 v42, v44, v43, v16
	v_med3_f32 v43, v45, v44, v16
	v_med3_f32 v44, v46, v45, v16
	v_med3_f32 v45, v47, v46, v16
	v_med3_f32 v46, v48, v47, v16
	v_med3_f32 v47, v49, v48, v16
	v_med3_f32 v48, v50, v49, v16
	v_med3_f32 v49, v34, v50, v16
	v_max_f32_e32 v16, v16, v16
	v_sub_u32_e32 v17, v17, v32
	v_max_f32_e32 v16, v34, v16
	v_add_u32_e32 v17, 62, v17
	v_med3_f32 v34, v36, v35, v17
	v_med3_f32 v35, v37, v36, v17
	v_med3_f32 v36, v38, v37, v17
	v_med3_f32 v37, v39, v38, v17
	v_med3_f32 v38, v40, v39, v17
	v_med3_f32 v39, v41, v40, v17
	v_med3_f32 v40, v42, v41, v17
	v_med3_f32 v41, v43, v42, v17
	v_med3_f32 v42, v44, v43, v17
	v_med3_f32 v43, v45, v44, v17
	v_med3_f32 v44, v46, v45, v17
	v_med3_f32 v45, v47, v46, v17
	v_med3_f32 v46, v48, v47, v17
	v_med3_f32 v47, v49, v48, v17
	v_med3_f32 v48, v16, v49, v17
	v_max_f32_e32 v17, v17, v17
	v_max_f32_e32 v16, v16, v17
	v_and_b32_e32 v17, 0xffffff80, v18
	v_sub_u32_e32 v17, v17, v32
	v_add_u32_e32 v17, 61, v17
	v_med3_f32 v18, v35, v34, v17
	v_med3_f32 v34, v36, v35, v17
	v_med3_f32 v35, v37, v36, v17
	v_med3_f32 v36, v38, v37, v17
	v_med3_f32 v37, v39, v38, v17
	v_med3_f32 v38, v40, v39, v17
	v_med3_f32 v39, v41, v40, v17
	v_med3_f32 v40, v42, v41, v17
	v_med3_f32 v41, v43, v42, v17
	v_med3_f32 v42, v44, v43, v17
	v_med3_f32 v43, v45, v44, v17
	v_med3_f32 v44, v46, v45, v17
	v_med3_f32 v45, v47, v46, v17
	v_med3_f32 v46, v48, v47, v17
	v_med3_f32 v47, v16, v48, v17
	v_max_f32_e32 v17, v17, v17
	v_max_f32_e32 v16, v16, v17
	v_and_b32_e32 v17, 0xffffff80, v19
	v_sub_u32_e32 v17, v17, v32
	v_add_u32_e32 v17, 60, v17
	v_med3_f32 v18, v34, v18, v17
	v_med3_f32 v19, v35, v34, v17
	v_med3_f32 v34, v36, v35, v17
	v_med3_f32 v35, v37, v36, v17
	v_med3_f32 v36, v38, v37, v17
	v_med3_f32 v37, v39, v38, v17
	v_med3_f32 v38, v40, v39, v17
	v_med3_f32 v39, v41, v40, v17
	v_med3_f32 v40, v42, v41, v17
	v_med3_f32 v41, v43, v42, v17
	v_med3_f32 v42, v44, v43, v17
	v_med3_f32 v43, v45, v44, v17
	v_med3_f32 v44, v46, v45, v17
	v_med3_f32 v45, v47, v46, v17
	v_med3_f32 v46, v16, v47, v17
	v_max_f32_e32 v17, v17, v17
	v_max_f32_e32 v16, v16, v17
	v_and_b32_e32 v17, 0xffffff80, v20
	v_sub_u32_e32 v17, v17, v32
	v_add_u32_e32 v17, 55, v17
	v_med3_f32 v18, v19, v18, v17
	v_med3_f32 v19, v34, v19, v17
	v_med3_f32 v20, v35, v34, v17
	v_med3_f32 v34, v36, v35, v17
	v_med3_f32 v35, v37, v36, v17
	v_med3_f32 v36, v38, v37, v17
	v_med3_f32 v37, v39, v38, v17
	v_med3_f32 v38, v40, v39, v17
	v_med3_f32 v39, v41, v40, v17
	v_med3_f32 v40, v42, v41, v17
	v_med3_f32 v41, v43, v42, v17
	v_med3_f32 v42, v44, v43, v17
	v_med3_f32 v43, v45, v44, v17
	v_med3_f32 v44, v46, v45, v17
	v_med3_f32 v45, v16, v46, v17
	v_max_f32_e32 v17, v17, v17
	v_max_f32_e32 v16, v16, v17
	v_and_b32_e32 v17, 0xffffff80, v21
	v_sub_u32_e32 v17, v17, v32
	v_add_u32_e32 v17, 54, v17
	v_med3_f32 v18, v19, v18, v17
	v_med3_f32 v19, v20, v19, v17
	v_med3_f32 v20, v34, v20, v17
	v_med3_f32 v21, v35, v34, v17
	v_med3_f32 v34, v36, v35, v17
	v_med3_f32 v35, v37, v36, v17
	v_med3_f32 v36, v38, v37, v17
	v_med3_f32 v37, v39, v38, v17
	v_med3_f32 v38, v40, v39, v17
	v_med3_f32 v39, v41, v40, v17
	v_med3_f32 v40, v42, v41, v17
	v_med3_f32 v41, v43, v42, v17
	v_med3_f32 v42, v44, v43, v17
	v_med3_f32 v43, v45, v44, v17
	v_med3_f32 v44, v16, v45, v17
	v_max_f32_e32 v17, v17, v17
	v_max_f32_e32 v16, v16, v17
	v_and_b32_e32 v17, 0xffffff80, v22
	v_sub_u32_e32 v17, v17, v32
	v_add_u32_e32 v17, 53, v17
	v_med3_f32 v18, v19, v18, v17
	v_med3_f32 v19, v20, v19, v17
	v_med3_f32 v20, v21, v20, v17
	v_med3_f32 v21, v34, v21, v17
	v_med3_f32 v22, v35, v34, v17
	v_med3_f32 v34, v36, v35, v17
	v_med3_f32 v35, v37, v36, v17
	v_med3_f32 v36, v38, v37, v17
	v_med3_f32 v37, v39, v38, v17
	v_med3_f32 v38, v40, v39, v17
	v_med3_f32 v39, v41, v40, v17
	v_med3_f32 v40, v42, v41, v17
	v_med3_f32 v41, v43, v42, v17
	v_med3_f32 v42, v44, v43, v17
	v_med3_f32 v43, v16, v44, v17
	v_max_f32_e32 v17, v17, v17
	v_max_f32_e32 v16, v16, v17
	v_and_b32_e32 v17, 0xffffff80, v23
	v_sub_u32_e32 v17, v17, v32
	v_add_u32_e32 v17, 52, v17
	v_med3_f32 v18, v19, v18, v17
	v_med3_f32 v19, v20, v19, v17
	v_med3_f32 v20, v21, v20, v17
	v_med3_f32 v21, v22, v21, v17
	v_med3_f32 v22, v34, v22, v17
	v_med3_f32 v23, v35, v34, v17
	v_med3_f32 v34, v36, v35, v17
	v_med3_f32 v35, v37, v36, v17
	v_med3_f32 v36, v38, v37, v17
	v_med3_f32 v37, v39, v38, v17
	v_med3_f32 v38, v40, v39, v17
	v_med3_f32 v39, v41, v40, v17
	v_med3_f32 v40, v42, v41, v17
	v_med3_f32 v41, v43, v42, v17
	v_med3_f32 v42, v16, v43, v17
	v_max_f32_e32 v17, v17, v17
	v_max_f32_e32 v16, v16, v17
	v_and_b32_e32 v17, 0xffffff80, v24
	v_sub_u32_e32 v17, v17, v32
	v_add_u32_e32 v17, 47, v17
	v_med3_f32 v18, v19, v18, v17
	v_med3_f32 v19, v20, v19, v17
	v_med3_f32 v20, v21, v20, v17
	v_med3_f32 v21, v22, v21, v17
	v_med3_f32 v22, v23, v22, v17
	v_med3_f32 v23, v34, v23, v17
	v_med3_f32 v24, v35, v34, v17
	v_med3_f32 v34, v36, v35, v17
	v_med3_f32 v35, v37, v36, v17
	v_med3_f32 v36, v38, v37, v17
	v_med3_f32 v37, v39, v38, v17
	v_med3_f32 v38, v40, v39, v17
	v_med3_f32 v39, v41, v40, v17
	v_med3_f32 v40, v42, v41, v17
	v_med3_f32 v41, v16, v42, v17
	v_max_f32_e32 v17, v17, v17
	v_max_f32_e32 v16, v16, v17
	v_and_b32_e32 v17, 0xffffff80, v25
	v_sub_u32_e32 v17, v17, v32
	v_add_u32_e32 v17, 46, v17
	v_med3_f32 v18, v19, v18, v17
	v_med3_f32 v19, v20, v19, v17
	v_med3_f32 v20, v21, v20, v17
	v_med3_f32 v21, v22, v21, v17
	v_med3_f32 v22, v23, v22, v17
	v_med3_f32 v23, v24, v23, v17
	v_med3_f32 v24, v34, v24, v17
	v_med3_f32 v25, v35, v34, v17
	v_med3_f32 v34, v36, v35, v17
	v_med3_f32 v35, v37, v36, v17
	v_med3_f32 v36, v38, v37, v17
	v_med3_f32 v37, v39, v38, v17
	v_med3_f32 v38, v40, v39, v17
	v_med3_f32 v39, v41, v40, v17
	v_med3_f32 v40, v16, v41, v17
	v_max_f32_e32 v17, v17, v17
	v_max_f32_e32 v16, v16, v17
	v_and_b32_e32 v17, 0xffffff80, v26
	v_sub_u32_e32 v17, v17, v32
	v_add_u32_e32 v17, 45, v17
	v_med3_f32 v18, v19, v18, v17
	v_med3_f32 v19, v20, v19, v17
	v_med3_f32 v20, v21, v20, v17
	v_med3_f32 v21, v22, v21, v17
	v_med3_f32 v22, v23, v22, v17
	v_med3_f32 v23, v24, v23, v17
	v_med3_f32 v24, v25, v24, v17
	v_med3_f32 v25, v34, v25, v17
	v_med3_f32 v26, v35, v34, v17
	v_med3_f32 v34, v36, v35, v17
	v_med3_f32 v35, v37, v36, v17
	v_med3_f32 v36, v38, v37, v17
	v_med3_f32 v37, v39, v38, v17
	v_med3_f32 v38, v40, v39, v17
	v_med3_f32 v39, v16, v40, v17
	v_max_f32_e32 v17, v17, v17
	v_max_f32_e32 v16, v16, v17
	v_and_b32_e32 v17, 0xffffff80, v27
	v_sub_u32_e32 v17, v17, v32
	v_add_u32_e32 v17, 44, v17
	v_med3_f32 v18, v19, v18, v17
	v_med3_f32 v19, v20, v19, v17
	v_med3_f32 v20, v21, v20, v17
	v_med3_f32 v21, v22, v21, v17
	v_med3_f32 v22, v23, v22, v17
	v_med3_f32 v23, v24, v23, v17
	v_med3_f32 v24, v25, v24, v17
	v_med3_f32 v25, v26, v25, v17
	v_med3_f32 v26, v34, v26, v17
	v_med3_f32 v27, v35, v34, v17
	v_med3_f32 v34, v36, v35, v17
	v_med3_f32 v35, v37, v36, v17
	v_med3_f32 v36, v38, v37, v17
	v_med3_f32 v37, v39, v38, v17
	v_med3_f32 v38, v16, v39, v17
	v_max_f32_e32 v17, v17, v17
	v_max_f32_e32 v16, v16, v17
	v_and_b32_e32 v17, 0xffffff80, v28
	v_sub_u32_e32 v17, v17, v32
	v_add_u32_e32 v17, 39, v17
	v_med3_f32 v18, v19, v18, v17
	v_med3_f32 v19, v20, v19, v17
	v_med3_f32 v20, v21, v20, v17
	v_med3_f32 v21, v22, v21, v17
	v_med3_f32 v22, v23, v22, v17
	v_med3_f32 v23, v24, v23, v17
	v_med3_f32 v24, v25, v24, v17
	v_med3_f32 v25, v26, v25, v17
	v_med3_f32 v26, v27, v26, v17
	v_med3_f32 v27, v34, v27, v17
	v_med3_f32 v28, v35, v34, v17
	v_med3_f32 v34, v36, v35, v17
	v_med3_f32 v35, v37, v36, v17
	v_med3_f32 v36, v38, v37, v17
	v_med3_f32 v37, v16, v38, v17
	v_max_f32_e32 v17, v17, v17
	v_max_f32_e32 v16, v16, v17
	v_and_b32_e32 v17, 0xffffff80, v29
	v_sub_u32_e32 v17, v17, v32
	v_add_u32_e32 v17, 38, v17
	v_med3_f32 v18, v19, v18, v17
	v_med3_f32 v19, v20, v19, v17
	v_med3_f32 v20, v21, v20, v17
	v_med3_f32 v21, v22, v21, v17
	v_med3_f32 v22, v23, v22, v17
	v_med3_f32 v23, v24, v23, v17
	v_med3_f32 v24, v25, v24, v17
	v_med3_f32 v25, v26, v25, v17
	v_med3_f32 v26, v27, v26, v17
	v_med3_f32 v27, v28, v27, v17
	v_med3_f32 v28, v34, v28, v17
	v_med3_f32 v29, v35, v34, v17
	v_med3_f32 v34, v36, v35, v17
	v_med3_f32 v35, v37, v36, v17
	v_med3_f32 v36, v16, v37, v17
	v_max_f32_e32 v17, v17, v17
	v_max_f32_e32 v16, v16, v17
	v_and_b32_e32 v17, 0xffffff80, v30
	v_sub_u32_e32 v17, v17, v32
	v_add_u32_e32 v17, 37, v17
	v_med3_f32 v18, v19, v18, v17
	v_med3_f32 v19, v20, v19, v17
	v_med3_f32 v20, v21, v20, v17
	v_med3_f32 v21, v22, v21, v17
	v_med3_f32 v22, v23, v22, v17
	v_med3_f32 v23, v24, v23, v17
	v_med3_f32 v24, v25, v24, v17
	v_med3_f32 v25, v26, v25, v17
	v_med3_f32 v26, v27, v26, v17
	v_med3_f32 v27, v28, v27, v17
	v_med3_f32 v28, v29, v28, v17
	v_med3_f32 v29, v34, v29, v17
	v_med3_f32 v30, v35, v34, v17
	v_med3_f32 v34, v36, v35, v17
	v_med3_f32 v35, v16, v36, v17
	v_max_f32_e32 v17, v17, v17
	v_max_f32_e32 v16, v16, v17
	v_and_b32_e32 v17, 0xffffff80, v31
	v_sub_u32_e32 v17, v17, v32
	v_add_u32_e32 v17, 36, v17
	v_med3_f32 v18, v19, v18, v17
	v_med3_f32 v19, v20, v19, v17
	v_med3_f32 v20, v21, v20, v17
	v_med3_f32 v21, v22, v21, v17
	v_med3_f32 v22, v23, v22, v17
	v_med3_f32 v23, v24, v23, v17
	v_med3_f32 v24, v25, v24, v17
	v_med3_f32 v25, v26, v25, v17
	v_med3_f32 v26, v27, v26, v17
	v_med3_f32 v27, v28, v27, v17
	v_med3_f32 v28, v29, v28, v17
	v_med3_f32 v29, v30, v29, v17
	v_med3_f32 v30, v34, v30, v17
	v_med3_f32 v31, v35, v34, v17
	v_med3_f32 v34, v16, v35, v17
	v_max_f32_e32 v17, v17, v17
	v_and_b32_e32 v0, 0xffffff80, v0
	v_max_f32_e32 v16, v16, v17
	v_bitop3_b32 v0, v0, 31, v32 bitop3:0x36
	v_and_b32_e32 v1, 0xffffff80, v1
	v_med3_f32 v17, v19, v18, v0
	v_med3_f32 v18, v20, v19, v0
	v_med3_f32 v19, v21, v20, v0
	v_med3_f32 v20, v22, v21, v0
	v_med3_f32 v21, v23, v22, v0
	v_med3_f32 v22, v24, v23, v0
	v_med3_f32 v23, v25, v24, v0
	v_med3_f32 v24, v26, v25, v0
	v_med3_f32 v25, v27, v26, v0
	v_med3_f32 v26, v28, v27, v0
	v_med3_f32 v27, v29, v28, v0
	v_med3_f32 v28, v30, v29, v0
	v_med3_f32 v29, v31, v30, v0
	v_med3_f32 v30, v34, v31, v0
	v_med3_f32 v31, v16, v34, v0
	v_max_f32_e32 v0, v0, v0
	v_sub_u32_e32 v1, v1, v32
	v_max_f32_e32 v0, v16, v0
	v_add_u32_e32 v1, 30, v1
	v_med3_f32 v16, v18, v17, v1
	v_med3_f32 v17, v19, v18, v1
	v_med3_f32 v18, v20, v19, v1
	v_med3_f32 v19, v21, v20, v1
	v_med3_f32 v20, v22, v21, v1
	v_med3_f32 v21, v23, v22, v1
	v_med3_f32 v22, v24, v23, v1
	v_med3_f32 v23, v25, v24, v1
	v_med3_f32 v24, v26, v25, v1
	v_med3_f32 v25, v27, v26, v1
	v_med3_f32 v26, v28, v27, v1
	v_med3_f32 v27, v29, v28, v1
	v_med3_f32 v28, v30, v29, v1
	v_med3_f32 v29, v31, v30, v1
	v_med3_f32 v30, v0, v31, v1
	v_max_f32_e32 v1, v1, v1
	v_max_f32_e32 v0, v0, v1
	v_and_b32_e32 v1, 0xffffff80, v2
	v_sub_u32_e32 v1, v1, v32
	v_add_u32_e32 v1, 29, v1
	v_med3_f32 v2, v17, v16, v1
	v_med3_f32 v16, v18, v17, v1
	v_med3_f32 v17, v19, v18, v1
	v_med3_f32 v18, v20, v19, v1
	v_med3_f32 v19, v21, v20, v1
	v_med3_f32 v20, v22, v21, v1
	v_med3_f32 v21, v23, v22, v1
	v_med3_f32 v22, v24, v23, v1
	v_med3_f32 v23, v25, v24, v1
	v_med3_f32 v24, v26, v25, v1
	v_med3_f32 v25, v27, v26, v1
	v_med3_f32 v26, v28, v27, v1
	v_med3_f32 v27, v29, v28, v1
	v_med3_f32 v28, v30, v29, v1
	v_med3_f32 v29, v0, v30, v1
	v_max_f32_e32 v1, v1, v1
	v_max_f32_e32 v0, v0, v1
	v_and_b32_e32 v1, 0xffffff80, v3
	v_sub_u32_e32 v1, v1, v32
	v_add_u32_e32 v1, 28, v1
	v_med3_f32 v2, v16, v2, v1
	v_med3_f32 v3, v17, v16, v1
	v_med3_f32 v16, v18, v17, v1
	v_med3_f32 v17, v19, v18, v1
	v_med3_f32 v18, v20, v19, v1
	v_med3_f32 v19, v21, v20, v1
	v_med3_f32 v20, v22, v21, v1
	v_med3_f32 v21, v23, v22, v1
	v_med3_f32 v22, v24, v23, v1
	v_med3_f32 v23, v25, v24, v1
	v_med3_f32 v24, v26, v25, v1
	v_med3_f32 v25, v27, v26, v1
	v_med3_f32 v26, v28, v27, v1
	v_med3_f32 v27, v29, v28, v1
	v_med3_f32 v28, v0, v29, v1
	v_max_f32_e32 v1, v1, v1
	v_max_f32_e32 v0, v0, v1
	v_and_b32_e32 v1, 0xffffff80, v4
	v_sub_u32_e32 v1, v1, v32
	v_add_u32_e32 v1, 23, v1
	v_med3_f32 v2, v3, v2, v1
	v_med3_f32 v3, v16, v3, v1
	v_med3_f32 v4, v17, v16, v1
	v_med3_f32 v16, v18, v17, v1
	v_med3_f32 v17, v19, v18, v1
	v_med3_f32 v18, v20, v19, v1
	v_med3_f32 v19, v21, v20, v1
	v_med3_f32 v20, v22, v21, v1
	v_med3_f32 v21, v23, v22, v1
	v_med3_f32 v22, v24, v23, v1
	v_med3_f32 v23, v25, v24, v1
	v_med3_f32 v24, v26, v25, v1
	v_med3_f32 v25, v27, v26, v1
	v_med3_f32 v26, v28, v27, v1
	v_med3_f32 v27, v0, v28, v1
	v_max_f32_e32 v1, v1, v1
	v_max_f32_e32 v0, v0, v1
	v_and_b32_e32 v1, 0xffffff80, v5
	v_sub_u32_e32 v1, v1, v32
	v_add_u32_e32 v1, 22, v1
	v_med3_f32 v2, v3, v2, v1
	v_med3_f32 v3, v4, v3, v1
	v_med3_f32 v4, v16, v4, v1
	v_med3_f32 v5, v17, v16, v1
	v_med3_f32 v16, v18, v17, v1
	v_med3_f32 v17, v19, v18, v1
	v_med3_f32 v18, v20, v19, v1
	v_med3_f32 v19, v21, v20, v1
	v_med3_f32 v20, v22, v21, v1
	v_med3_f32 v21, v23, v22, v1
	v_med3_f32 v22, v24, v23, v1
	v_med3_f32 v23, v25, v24, v1
	v_med3_f32 v24, v26, v25, v1
	v_med3_f32 v25, v27, v26, v1
	v_med3_f32 v26, v0, v27, v1
	v_max_f32_e32 v1, v1, v1
	v_max_f32_e32 v0, v0, v1
	v_and_b32_e32 v1, 0xffffff80, v6
	v_sub_u32_e32 v1, v1, v32
	v_add_u32_e32 v1, 21, v1
	v_med3_f32 v2, v3, v2, v1
	v_med3_f32 v3, v4, v3, v1
	v_med3_f32 v4, v5, v4, v1
	v_med3_f32 v5, v16, v5, v1
	v_med3_f32 v6, v17, v16, v1
	v_med3_f32 v16, v18, v17, v1
	v_med3_f32 v17, v19, v18, v1
	v_med3_f32 v18, v20, v19, v1
	v_med3_f32 v19, v21, v20, v1
	v_med3_f32 v20, v22, v21, v1
	v_med3_f32 v21, v23, v22, v1
	v_med3_f32 v22, v24, v23, v1
	v_med3_f32 v23, v25, v24, v1
	v_med3_f32 v24, v26, v25, v1
	v_med3_f32 v25, v0, v26, v1
	v_max_f32_e32 v1, v1, v1
	v_max_f32_e32 v0, v0, v1
	v_and_b32_e32 v1, 0xffffff80, v7
	v_sub_u32_e32 v1, v1, v32
	v_add_u32_e32 v1, 20, v1
	v_med3_f32 v2, v3, v2, v1
	v_med3_f32 v3, v4, v3, v1
	v_med3_f32 v4, v5, v4, v1
	v_med3_f32 v5, v6, v5, v1
	v_med3_f32 v6, v16, v6, v1
	v_med3_f32 v7, v17, v16, v1
	v_med3_f32 v16, v18, v17, v1
	v_med3_f32 v17, v19, v18, v1
	v_med3_f32 v18, v20, v19, v1
	v_med3_f32 v19, v21, v20, v1
	v_med3_f32 v20, v22, v21, v1
	v_med3_f32 v21, v23, v22, v1
	v_med3_f32 v22, v24, v23, v1
	v_med3_f32 v23, v25, v24, v1
	v_med3_f32 v24, v0, v25, v1
	v_max_f32_e32 v1, v1, v1
	v_max_f32_e32 v0, v0, v1
	v_and_b32_e32 v1, 0xffffff80, v8
	v_bitop3_b32 v1, v1, 15, v32 bitop3:0x36
	v_med3_f32 v2, v3, v2, v1
	v_med3_f32 v3, v4, v3, v1
	v_med3_f32 v4, v5, v4, v1
	v_med3_f32 v5, v6, v5, v1
	v_med3_f32 v6, v7, v6, v1
	v_med3_f32 v7, v16, v7, v1
	v_med3_f32 v8, v17, v16, v1
	v_med3_f32 v16, v18, v17, v1
	v_med3_f32 v17, v19, v18, v1
	v_med3_f32 v18, v20, v19, v1
	v_med3_f32 v19, v21, v20, v1
	v_med3_f32 v20, v22, v21, v1
	v_med3_f32 v21, v23, v22, v1
	v_med3_f32 v22, v24, v23, v1
	v_med3_f32 v23, v0, v24, v1
	v_max_f32_e32 v1, v1, v1
	v_max_f32_e32 v0, v0, v1
	v_and_b32_e32 v1, 0xffffff80, v9
	v_sub_u32_e32 v1, v1, v32
	v_add_u32_e32 v1, 14, v1
	v_med3_f32 v2, v3, v2, v1
	v_med3_f32 v3, v4, v3, v1
	v_med3_f32 v4, v5, v4, v1
	v_med3_f32 v5, v6, v5, v1
	v_med3_f32 v6, v7, v6, v1
	v_med3_f32 v7, v8, v7, v1
	v_med3_f32 v8, v16, v8, v1
	v_med3_f32 v9, v17, v16, v1
	v_med3_f32 v16, v18, v17, v1
	v_med3_f32 v17, v19, v18, v1
	v_med3_f32 v18, v20, v19, v1
	v_med3_f32 v19, v21, v20, v1
	v_med3_f32 v20, v22, v21, v1
	v_med3_f32 v21, v23, v22, v1
	v_med3_f32 v22, v0, v23, v1
	v_max_f32_e32 v1, v1, v1
	v_max_f32_e32 v0, v0, v1
	v_and_b32_e32 v1, 0xffffff80, v10
	v_sub_u32_e32 v1, v1, v32
	v_add_u32_e32 v1, 13, v1
	v_med3_f32 v2, v3, v2, v1
	v_med3_f32 v3, v4, v3, v1
	v_med3_f32 v4, v5, v4, v1
	v_med3_f32 v5, v6, v5, v1
	v_med3_f32 v6, v7, v6, v1
	v_med3_f32 v7, v8, v7, v1
	v_med3_f32 v8, v9, v8, v1
	v_med3_f32 v9, v16, v9, v1
	v_med3_f32 v10, v17, v16, v1
	v_med3_f32 v16, v18, v17, v1
	v_med3_f32 v17, v19, v18, v1
	v_med3_f32 v18, v20, v19, v1
	v_med3_f32 v19, v21, v20, v1
	v_med3_f32 v20, v22, v21, v1
	v_med3_f32 v21, v0, v22, v1
	v_max_f32_e32 v1, v1, v1
	v_max_f32_e32 v0, v0, v1
	v_and_b32_e32 v1, 0xffffff80, v11
	v_sub_u32_e32 v1, v1, v32
	v_add_u32_e32 v1, 12, v1
	v_med3_f32 v2, v3, v2, v1
	v_med3_f32 v3, v4, v3, v1
	v_med3_f32 v4, v5, v4, v1
	v_med3_f32 v5, v6, v5, v1
	v_med3_f32 v6, v7, v6, v1
	v_med3_f32 v7, v8, v7, v1
	v_med3_f32 v8, v9, v8, v1
	v_med3_f32 v9, v10, v9, v1
	v_med3_f32 v10, v16, v10, v1
	v_med3_f32 v11, v17, v16, v1
	v_med3_f32 v16, v18, v17, v1
	v_med3_f32 v17, v19, v18, v1
	v_med3_f32 v18, v20, v19, v1
	v_med3_f32 v19, v21, v20, v1
	v_med3_f32 v20, v0, v21, v1
	v_max_f32_e32 v1, v1, v1
	v_max_f32_e32 v0, v0, v1
	v_and_b32_e32 v1, 0xffffff80, v12
	v_bitop3_b32 v1, v1, 7, v32 bitop3:0x36
	v_med3_f32 v2, v3, v2, v1
	v_med3_f32 v3, v4, v3, v1
	v_med3_f32 v4, v5, v4, v1
	v_med3_f32 v5, v6, v5, v1
	v_med3_f32 v6, v7, v6, v1
	v_med3_f32 v7, v8, v7, v1
	v_med3_f32 v8, v9, v8, v1
	v_med3_f32 v9, v10, v9, v1
	v_med3_f32 v10, v11, v10, v1
	v_med3_f32 v11, v16, v11, v1
	v_med3_f32 v12, v17, v16, v1
	v_med3_f32 v16, v18, v17, v1
	v_med3_f32 v17, v19, v18, v1
	v_med3_f32 v18, v20, v19, v1
	v_med3_f32 v19, v0, v20, v1
	v_max_f32_e32 v1, v1, v1
	v_max_f32_e32 v0, v0, v1
	v_and_b32_e32 v1, 0xffffff80, v13
	v_sub_u32_e32 v1, v1, v32
	v_add_u32_e32 v1, 6, v1
	v_med3_f32 v2, v3, v2, v1
	v_med3_f32 v3, v4, v3, v1
	v_med3_f32 v4, v5, v4, v1
	v_med3_f32 v5, v6, v5, v1
	v_med3_f32 v6, v7, v6, v1
	v_med3_f32 v7, v8, v7, v1
	v_med3_f32 v8, v9, v8, v1
	v_med3_f32 v9, v10, v9, v1
	v_med3_f32 v10, v11, v10, v1
	v_med3_f32 v11, v12, v11, v1
	v_med3_f32 v12, v16, v12, v1
	v_med3_f32 v13, v17, v16, v1
	v_med3_f32 v16, v18, v17, v1
	v_med3_f32 v17, v19, v18, v1
	v_med3_f32 v18, v0, v19, v1
	v_max_f32_e32 v1, v1, v1
	v_max_f32_e32 v0, v0, v1
	v_and_b32_e32 v1, 0xffffff80, v14
	v_sub_u32_e32 v1, v1, v32
	v_add_u32_e32 v1, 5, v1
	v_med3_f32 v2, v3, v2, v1
	v_med3_f32 v3, v4, v3, v1
	v_med3_f32 v14, v5, v4, v1
	v_med3_f32 v19, v6, v5, v1
	v_med3_f32 v20, v7, v6, v1
	v_med3_f32 v7, v8, v7, v1
	v_med3_f32 v8, v9, v8, v1
	v_med3_f32 v9, v10, v9, v1
	v_med3_f32 v10, v11, v10, v1
	v_med3_f32 v11, v12, v11, v1
	v_med3_f32 v12, v13, v12, v1
	v_med3_f32 v13, v16, v13, v1
	v_med3_f32 v16, v17, v16, v1
	v_med3_f32 v17, v18, v17, v1
	v_med3_f32 v18, v0, v18, v1
	v_max_f32_e32 v1, v1, v1
	v_max_f32_e32 v0, v0, v1
	v_and_b32_e32 v1, 0xffffff80, v15
	v_sub_u32_e32 v1, v1, v32
	v_add_u32_e32 v1, 4, v1
	v_med3_f32 v4, v3, v2, v1
	v_med3_f32 v5, v14, v3, v1
	v_med3_f32 v6, v19, v14, v1
	v_med3_f32 v23, v20, v19, v1
	v_med3_f32 v24, v7, v20, v1
	v_med3_f32 v25, v8, v7, v1
	v_med3_f32 v26, v9, v8, v1
	v_med3_f32 v27, v10, v9, v1
	v_med3_f32 v28, v11, v10, v1
	v_med3_f32 v29, v12, v11, v1
	v_med3_f32 v30, v13, v12, v1
	v_med3_f32 v31, v16, v13, v1
	v_med3_f32 v32, v17, v16, v1
	v_med3_f32 v3, v18, v17, v1
	v_med3_f32 v2, v0, v18, v1
	v_max_f32_e32 v1, v1, v1
	v_and_b32_e32 v7, 64, v214
	v_max_f32_e32 v1, v0, v1
	v_xor_b32_e32 v0, 32, v214
	v_add_u32_e32 v7, 64, v7
	v_cmp_lt_i32_e32 vcc, v0, v7
	s_nop 1
	v_cndmask_b32_e32 v0, v214, v0, vcc
	v_lshlrev_b32_e32 v0, 2, v0
	ds_bpermute_b32 v7, v0, v1
	ds_bpermute_b32 v8, v0, v2
	ds_bpermute_b32 v9, v0, v3
	ds_bpermute_b32 v10, v0, v32
	ds_bpermute_b32 v11, v0, v31
	ds_bpermute_b32 v12, v0, v30
	ds_bpermute_b32 v13, v0, v29
	ds_bpermute_b32 v14, v0, v28
	ds_bpermute_b32 v15, v0, v27
	ds_bpermute_b32 v16, v0, v26
	ds_bpermute_b32 v17, v0, v25
	ds_bpermute_b32 v18, v0, v24
	ds_bpermute_b32 v19, v0, v23
	ds_bpermute_b32 v20, v0, v6
	ds_bpermute_b32 v21, v0, v5
	ds_bpermute_b32 v22, v0, v4
	v_cmp_gt_u32_e32 vcc, 32, v130
	s_and_saveexec_b64 s[8:9], vcc
	s_cbranch_execz .LBB0_1861
	s_waitcnt lgkmcnt(0)
	v_max_f32_e32 v34, v1, v22
	v_max_f32_e32 v35, v2, v21
	v_max_f32_e32 v36, v3, v20
	v_max_f32_e32 v37, v32, v19
	v_max_f32_e32 v38, v31, v18
	v_max_f32_e32 v39, v30, v17
	v_max_f32_e32 v40, v29, v16
	v_max_f32_e32 v41, v28, v15
	v_max_f32_e32 v42, v27, v14
	v_max_f32_e32 v43, v26, v13
	v_max_f32_e32 v44, v25, v12
	v_max_f32_e32 v45, v24, v11
	v_max_f32_e32 v46, v23, v10
	v_max_f32_e32 v47, v6, v9
	v_max_f32_e32 v48, v5, v8
	v_max_f32_e32 v49, v4, v7
	v_max_f32_e32 v7, v34, v42
	v_min_f32_e32 v15, v34, v42
	v_max_f32_e32 v8, v35, v43
	v_min_f32_e32 v16, v35, v43
	v_max_f32_e32 v9, v36, v44
	v_min_f32_e32 v17, v36, v44
	v_max_f32_e32 v10, v37, v45
	v_min_f32_e32 v18, v37, v45
	v_max_f32_e32 v11, v38, v46
	v_min_f32_e32 v19, v38, v46
	v_max_f32_e32 v12, v39, v47
	v_min_f32_e32 v20, v39, v47
	v_max_f32_e32 v13, v40, v48
	v_min_f32_e32 v21, v40, v48
	v_max_f32_e32 v14, v41, v49
	v_min_f32_e32 v22, v41, v49
	v_max_f32_e32 v34, v7, v11
	v_min_f32_e32 v38, v7, v11
	v_max_f32_e32 v35, v8, v12
	v_min_f32_e32 v39, v8, v12
	v_max_f32_e32 v36, v9, v13
	v_min_f32_e32 v40, v9, v13
	v_max_f32_e32 v37, v10, v14
	v_min_f32_e32 v41, v10, v14
	v_max_f32_e32 v42, v15, v19
	v_min_f32_e32 v46, v15, v19
	v_max_f32_e32 v43, v16, v20
	v_min_f32_e32 v47, v16, v20
	v_max_f32_e32 v44, v17, v21
	v_min_f32_e32 v48, v17, v21
	v_max_f32_e32 v45, v18, v22
	v_min_f32_e32 v49, v18, v22
	v_max_f32_e32 v7, v34, v36
	v_min_f32_e32 v9, v34, v36
	v_max_f32_e32 v8, v35, v37
	v_min_f32_e32 v10, v35, v37
	v_max_f32_e32 v11, v38, v40
	v_min_f32_e32 v13, v38, v40
	v_max_f32_e32 v12, v39, v41
	v_min_f32_e32 v14, v39, v41
	v_max_f32_e32 v15, v42, v44
	v_min_f32_e32 v17, v42, v44
	v_max_f32_e32 v16, v43, v45
	v_min_f32_e32 v18, v43, v45
	v_max_f32_e32 v19, v46, v48
	v_min_f32_e32 v21, v46, v48
	v_max_f32_e32 v20, v47, v49
	v_min_f32_e32 v22, v47, v49
	v_max_f32_e32 v0, v7, v8
	v_min_f32_e32 v1, v7, v8
	v_max_f32_e32 v2, v9, v10
	v_min_f32_e32 v3, v9, v10
	v_max_f32_e32 v34, v11, v12
	v_min_f32_e32 v35, v11, v12
	v_max_f32_e32 v36, v13, v14
	v_min_f32_e32 v37, v13, v14
	v_max_f32_e32 v28, v15, v16
	v_min_f32_e32 v29, v15, v16
	v_max_f32_e32 v30, v17, v18
	v_min_f32_e32 v31, v17, v18
	v_max_f32_e32 v24, v19, v20
	v_min_f32_e32 v25, v19, v20
	v_max_f32_e32 v26, v21, v22
	v_min_f32_e32 v27, v21, v22
	v_ashrrev_i32_e32 v4, 1, v186
	v_and_b32_e32 v4, 0xffffffe0, v4
	v_lshl_add_u32 v4, s2, 7, v4
	v_or_b32_e32 v4, v4, v130
	v_ashrrev_i32_e32 v5, 31, v4
	v_readlane_b32 s20, v248, 0
	v_lshlrev_b64 v[4:5], 10, v[4:5]
	v_readlane_b32 s21, v248, 1
	s_lshl_b64 s[4:5], s[4:5], 6
	v_lshl_add_u64 v[4:5], s[20:21], 0, v[4:5]
	v_readlane_b32 s20, v249, 14
	v_readlane_b32 s21, v249, 15
	v_lshl_add_u64 v[4:5], v[4:5], 0, s[4:5]
	v_readlane_b32 s22, v248, 2
	v_readlane_b32 s23, v248, 3
	v_readlane_b32 s24, v248, 4
	v_readlane_b32 s25, v248, 5
	v_readlane_b32 s26, v248, 6
	v_readlane_b32 s27, v248, 7
	global_store_dwordx4 v[4:5], v[0:3], off
	global_store_dwordx4 v[4:5], v[34:37], off offset:16
	global_store_dwordx4 v[4:5], v[28:31], off offset:32
	global_store_dwordx4 v[4:5], v[24:27], off offset:48
